# v046_pksum
# baseline (speedup 1.0000x reference)
.LBB0_327:
	v_exp_f32_e32 v116, v96
	v_exp_f32_e32 v117, v97
	v_exp_f32_e32 v118, v98
	v_exp_f32_e32 v119, v99
	v_exp_f32_e32 v120, v100
	v_exp_f32_e32 v121, v101
	v_exp_f32_e32 v122, v102
	v_exp_f32_e32 v123, v103
	v_cvt_pk_bf16_f32 v96, v116, v117
	v_cvt_pk_bf16_f32 v97, v118, v119
	v_cvt_pk_bf16_f32 v98, v120, v121
	v_cvt_pk_bf16_f32 v99, v122, v123
	s_waitcnt lgkmcnt(4)
	s_nop 0
	v_mfma_f32_32x32x16_bf16 v[48:63], v[10:13], v[96:99], v[48:63]
	s_waitcnt lgkmcnt(2)
	v_mfma_f32_32x32x16_bf16 v[32:47], v[6:9], v[96:99], v[32:47]
	ds_read_b64_tr_b16 v[6:7], v14 offset:53248
	ds_read_b64_tr_b16 v[8:9], v15 offset:53248
	ds_read_b64_tr_b16 v[10:11], v202 offset:53248
	ds_read_b64_tr_b16 v[12:13], v203 offset:53248
	ds_read_b64_tr_b16 v[100:101], v204 offset:53248
	ds_read_b64_tr_b16 v[102:103], v205 offset:53248
	ds_read_b64_tr_b16 v[112:113], v206 offset:53248
	ds_read_b64_tr_b16 v[114:115], v207 offset:53248
	v_mfma_f32_32x32x16_bf16 v[64:79], v[160:163], v[96:99], v[64:79]
	s_waitcnt lgkmcnt(8)
	v_mfma_f32_32x32x16_bf16 v[16:31], v[2:5], v[96:99], v[16:31]
	v_exp_f32_e32 v104, v104
	v_exp_f32_e32 v105, v105
	v_exp_f32_e32 v106, v106
	v_exp_f32_e32 v107, v107
	v_exp_f32_e32 v108, v108
	v_exp_f32_e32 v109, v109
	v_exp_f32_e32 v110, v110
	v_exp_f32_e32 v111, v111
	v_cvt_pk_bf16_f32 v2, v104, v105
	v_cvt_pk_bf16_f32 v3, v106, v107
	v_cvt_pk_bf16_f32 v4, v108, v109
	v_cvt_pk_bf16_f32 v5, v110, v111
	s_waitcnt lgkmcnt(6)
	s_nop 0
	v_mfma_f32_32x32x16_bf16 v[64:79], v[6:9], v[2:5], v[64:79]
	s_waitcnt lgkmcnt(4)
	v_mfma_f32_32x32x16_bf16 v[48:63], v[10:13], v[2:5], v[48:63]
	s_waitcnt lgkmcnt(2)
	v_mfma_f32_32x32x16_bf16 v[32:47], v[100:103], v[2:5], v[32:47]
	ds_read_b64_tr_b16 v[6:7], v14 offset:57344
	ds_read_b64_tr_b16 v[8:9], v15 offset:57344
	ds_read_b64_tr_b16 v[10:11], v202 offset:57344
	ds_read_b64_tr_b16 v[12:13], v203 offset:57344
	ds_read_b64_tr_b16 v[96:97], v204 offset:57344
	ds_read_b64_tr_b16 v[98:99], v205 offset:57344
	ds_read_b64_tr_b16 v[100:101], v206 offset:57344
	ds_read_b64_tr_b16 v[102:103], v207 offset:57344
	s_waitcnt lgkmcnt(8)
	v_mfma_f32_32x32x16_bf16 v[16:31], v[112:115], v[2:5], v[16:31]
	v_exp_f32_e32 v112, v80
	v_exp_f32_e32 v113, v81
	v_exp_f32_e32 v114, v82
	v_exp_f32_e32 v115, v83
	v_exp_f32_e32 v124, v84
	v_exp_f32_e32 v125, v85
	v_exp_f32_e32 v126, v86
	v_exp_f32_e32 v127, v87
	v_cvt_pk_bf16_f32 v2, v112, v113
	v_cvt_pk_bf16_f32 v3, v114, v115
	v_cvt_pk_bf16_f32 v4, v124, v125
	v_cvt_pk_bf16_f32 v5, v126, v127
	s_waitcnt lgkmcnt(6)
	s_nop 0
	v_mfma_f32_32x32x16_bf16 v[64:79], v[6:9], v[2:5], v[64:79]
	s_waitcnt lgkmcnt(4)
	v_mfma_f32_32x32x16_bf16 v[48:63], v[10:13], v[2:5], v[48:63]
	ds_read_b64_tr_b16 v[6:7], v14 offset:61440
	ds_read_b64_tr_b16 v[8:9], v15 offset:61440
	ds_read_b64_tr_b16 v[10:11], v202 offset:61440
	ds_read_b64_tr_b16 v[12:13], v203 offset:61440
	ds_read_b64_tr_b16 v[80:81], v204 offset:61440
	ds_read_b64_tr_b16 v[82:83], v205 offset:61440
	ds_read_b64_tr_b16 v[84:85], v206 offset:61440
	ds_read_b64_tr_b16 v[86:87], v207 offset:61440
	s_waitcnt lgkmcnt(10)
	v_mfma_f32_32x32x16_bf16 v[32:47], v[96:99], v[2:5], v[32:47]
	s_waitcnt lgkmcnt(8)
	v_mfma_f32_32x32x16_bf16 v[16:31], v[100:103], v[2:5], v[16:31]
	v_exp_f32_e32 v14, v88
	v_exp_f32_e32 v15, v89
	v_exp_f32_e32 v88, v90
	v_exp_f32_e32 v89, v91
	v_exp_f32_e32 v90, v92
	v_exp_f32_e32 v91, v93
	v_exp_f32_e32 v92, v94
	v_exp_f32_e32 v93, v95
	v_cvt_pk_bf16_f32 v2, v14, v15
	v_cvt_pk_bf16_f32 v3, v88, v89
	v_cvt_pk_bf16_f32 v4, v90, v91
	v_cvt_pk_bf16_f32 v5, v92, v93
	s_waitcnt lgkmcnt(6)
	s_nop 0
	v_mfma_f32_32x32x16_bf16 v[64:79], v[6:9], v[2:5], v[64:79]
	v_pk_add_f32 v[116:117], v[116:117], v[118:119]
	v_pk_add_f32 v[116:117], v[116:117], v[120:121]
	v_pk_add_f32 v[116:117], v[116:117], v[122:123]
	v_pk_add_f32 v[116:117], v[116:117], v[104:105]
	v_pk_add_f32 v[116:117], v[116:117], v[106:107]
	v_pk_add_f32 v[116:117], v[116:117], v[108:109]
	v_pk_add_f32 v[116:117], v[116:117], v[110:111]
	s_waitcnt lgkmcnt(4)
	v_mfma_f32_32x32x16_bf16 v[48:63], v[10:13], v[2:5], v[48:63]
	s_waitcnt lgkmcnt(2)
	v_mfma_f32_32x32x16_bf16 v[32:47], v[80:83], v[2:5], v[32:47]
	s_waitcnt lgkmcnt(0)
	v_mfma_f32_32x32x16_bf16 v[16:31], v[84:87], v[2:5], v[16:31]
	v_pk_add_f32 v[112:113], v[112:113], v[114:115]
	v_pk_add_f32 v[112:113], v[112:113], v[124:125]
	v_pk_add_f32 v[112:113], v[112:113], v[126:127]
	v_pk_add_f32 v[112:113], v[112:113], v[14:15]
	v_pk_add_f32 v[112:113], v[112:113], v[88:89]
	v_pk_add_f32 v[112:113], v[112:113], v[90:91]
	v_pk_add_f32 v[112:113], v[112:113], v[92:93]
	v_pk_add_f32 v[116:117], v[116:117], v[112:113]
	s_nop 0
	v_add_f32_e32 v2, v116, v117
	s_andn2_b64 vcc, exec, s[12:13]
	v_add_f32_e32 v201, v0, v2
	s_cbranch_vccnz .LBB0_331
	s_cmp_eq_u32 s82, 2
	s_cselect_b32 s12, s51, s22
	s_lshl_b32 s12, s12, 7
	s_lshl_b32 s13, s51, 7
	s_sub_i32 s12, s12, s24
	v_log_f32_e32 v0, v201
	s_addk_i32 s12, 0x80
	s_sub_i32 s13, s50, s13
	v_cvt_f32_i32_e32 v3, s13
	v_cvt_f32_i32_e32 v2, s12
	v_add_f32_e32 v0, v180, v0
	s_mov_b32 s12, 0xc21044fe
	v_sub_f32_e32 v0, v197, v0
	v_pk_fma_f32 v[2:3], v[176:177], v[2:3], s[12:13] op_sel_hi:[1,1,0]
	s_nop 0
	v_cmp_gt_f32_e64 s[40:41], v0, v3
	v_cmp_gt_f32_e32 vcc, v0, v2
	s_and_saveexec_b64 s[12:13], s[38:39]
	s_cbranch_execz .LBB0_330
	s_and_b32 s14, s83, 8
	s_lshl_b32 s14, s14, 2
	s_add_i32 s16, s48, s14
	s_cmp_lg_u64 s[40:41], 0
	s_cselect_b64 s[14:15], -1, 0
	s_cmp_eq_u64 vcc, 0
	v_cndmask_b32_e64 v0, 0, 1, s[14:15]
	s_cselect_b32 s14, 0, 2
	v_or_b32_e32 v0, s14, v0
	v_mov_b32_e32 v2, s16
	ds_write_b32 v2, v0

.Lmy_fast1_sum:
	v_pk_add_f32 v[212:213], v[212:213], v[214:215]
	v_pk_add_f32 v[246:247], v[246:247], v[248:249]
	v_pk_add_f32 v[212:213], v[212:213], v[216:217]
	v_pk_add_f32 v[246:247], v[246:247], v[250:251]
	v_pk_add_f32 v[212:213], v[212:213], v[218:219]
	v_pk_add_f32 v[246:247], v[246:247], v[232:233]
	v_pk_add_f32 v[212:213], v[212:213], v[220:221]
	v_pk_add_f32 v[246:247], v[246:247], v[234:235]
	v_pk_add_f32 v[212:213], v[212:213], v[222:223]
	v_pk_add_f32 v[246:247], v[246:247], v[236:237]
	v_pk_add_f32 v[212:213], v[212:213], v[224:225]
	v_pk_add_f32 v[246:247], v[246:247], v[238:239]
	v_add_f32_e32 v0, v228, v252
	v_add_f32_e32 v0, v231, v0
	v_add_f32_e32 v0, v240, v0
	v_add_f32_e32 v0, v201, v0
	v_pk_add_f32 v[212:213], v[212:213], v[246:247]
	s_nop 0
	v_add_f32_e32 v0, v212, v0
	v_add_f32_e32 v0, v213, v0
	s_branch .LBB0_327
